# attention online softmax: running reference only updated when a row max exceeds it by more than 4 in the log2 domain (exact by shift invariance), O rescale skipped otherwise
# speedup vs baseline: 1.0156x; 1.0056x over previous
; DI void attn_block(const AttnItem& it, int key0, int qi, int hh, const bf16x8 (&bq)[4], LAS unsigned char* Kl, LAS unsigned char* Vl, unsigned kr, unsigned vr,
;                    float& mrun, float& lsum, f32x16& o0, f32x16& o1) {
;     ...
;     float mx = s[0];
; #pragma unroll
;     for (int r = 1; r < 16; ++r) mx = fmaxf(mx, s[r]);
;     mx = fmaxf(mx, __shfl_xor(mx, 32));
;     const float mnew = fmaxf(mrun, mx);
;     const float alpha = __builtin_amdgcn_exp2f(mrun - mnew);
;     mrun = mnew;
;     float rs = 0.f;
; #pragma unroll
;     for (int r = 0; r < 16; ++r) { s[r] = __builtin_amdgcn_exp2f(s[r] - mnew); rs += s[r]; }
;     lsum = lsum * alpha + rs;
; #pragma unroll
;     for (int r = 0; r < 16; ++r) { o0[r] *= alpha; o1[r] *= alpha; }
.Lat_nomask_11:
	v_max3_f32 v96, v48, v49, v50
	v_max3_f32 v97, v51, v52, v53
	v_max3_f32 v96, v96, v54, v55
	v_max3_f32 v97, v97, v56, v57
	v_max3_f32 v96, v96, v58, v59
	v_max3_f32 v97, v97, v60, v61
	v_max3_f32 v96, v96, v62, v63
	v_max_f32_e32 v96, v96, v97
	v_mov_b32_e32 v97, v96
	s_nop 1
	v_permlane32_swap_b32_e32 v96, v97
	v_max_f32_e32 v96, v96, v97
	v_add_f32_e32 v96, s83, v96
	v_sub_f32_e32 v97, v96, v98
	v_cmp_lt_f32_e32 vcc, 4.0, v97
	s_cbranch_vccz .Lat_noupd_14
	v_max_f32_e32 v96, v98, v96
	v_sub_f32_e32 v100, v98, v96
	v_exp_f32_e32 v100, v100
	v_mov_b32_e32 v98, v96
	v_mul_f32_e32 v99, v99, v100
	v_mul_f32_e32 v16, v100, v16
	v_mul_f32_e32 v32, v100, v32
	v_mul_f32_e32 v17, v100, v17
	v_mul_f32_e32 v33, v100, v33
	v_mul_f32_e32 v18, v100, v18
	v_mul_f32_e32 v34, v100, v34
	v_mul_f32_e32 v19, v100, v19
	v_mul_f32_e32 v35, v100, v35
	v_mul_f32_e32 v20, v100, v20
	v_mul_f32_e32 v36, v100, v36
	v_mul_f32_e32 v21, v100, v21
	v_mul_f32_e32 v37, v100, v37
	v_mul_f32_e32 v22, v100, v22
	v_mul_f32_e32 v38, v100, v38
	v_mul_f32_e32 v23, v100, v23
	v_mul_f32_e32 v39, v100, v39
	v_mul_f32_e32 v24, v100, v24
	v_mul_f32_e32 v40, v100, v40
	v_mul_f32_e32 v25, v100, v25
	v_mul_f32_e32 v41, v100, v41
	v_mul_f32_e32 v26, v100, v26
	v_mul_f32_e32 v42, v100, v42
	v_mul_f32_e32 v27, v100, v27
	v_mul_f32_e32 v43, v100, v43
	v_mul_f32_e32 v28, v100, v28
	v_mul_f32_e32 v44, v100, v44
	v_mul_f32_e32 v29, v100, v29
	v_mul_f32_e32 v45, v100, v45
	v_mul_f32_e32 v30, v100, v30
	v_mul_f32_e32 v46, v100, v46
	v_mul_f32_e32 v31, v100, v31
	v_mul_f32_e32 v47, v100, v47
.Lat_noupd_14:
	v_sub_f32_e32 v101, s83, v98
	s_cmp_lt_u32 s79, s65
	s_cbranch_scc0 .Lat_nomfma_13
	s_waitcnt lgkmcnt(0)
	v_mfma_f32_32x32x16_bf16 v[64:79], v[80:83], v[0:3], 0
	v_mfma_f32_32x32x16_bf16 v[64:79], v[84:87], v[4:7], v[64:79]
	v_mfma_f32_32x32x16_bf16 v[64:79], v[88:91], v[8:11], v[64:79]
	v_mfma_f32_32x32x16_bf16 v[64:79], v[92:95], v[12:15], v[64:79]
.Lat_nomfma_13:
	v_add_f32_e32 v48, v101, v48
	v_add_f32_e32 v49, v101, v49
	v_add_f32_e32 v50, v101, v50
	v_add_f32_e32 v51, v101, v51
	v_add_f32_e32 v52, v101, v52
	v_add_f32_e32 v53, v101, v53
	v_add_f32_e32 v54, v101, v54
	v_add_f32_e32 v55, v101, v55
	v_add_f32_e32 v56, v101, v56
	v_add_f32_e32 v57, v101, v57
	v_add_f32_e32 v58, v101, v58
	v_add_f32_e32 v59, v101, v59
	v_add_f32_e32 v60, v101, v60
	v_add_f32_e32 v61, v101, v61
	v_add_f32_e32 v62, v101, v62
	v_add_f32_e32 v63, v101, v63
	v_exp_f32_e32 v48, v48
	v_exp_f32_e32 v49, v49
	v_exp_f32_e32 v50, v50
	v_exp_f32_e32 v51, v51
	v_exp_f32_e32 v52, v52
	v_exp_f32_e32 v53, v53
	v_exp_f32_e32 v54, v54
	v_exp_f32_e32 v55, v55
	v_exp_f32_e32 v56, v56
	v_exp_f32_e32 v57, v57
	v_exp_f32_e32 v58, v58
	v_exp_f32_e32 v59, v59
	v_exp_f32_e32 v60, v60
	v_exp_f32_e32 v61, v61
	v_exp_f32_e32 v62, v62
	v_exp_f32_e32 v63, v63
	v_add_f32_e32 v102, v48, v49
	v_add_f32_e32 v103, v50, v51
	v_add_f32_e32 v102, v102, v52
	v_add_f32_e32 v103, v103, v53
	v_add_f32_e32 v102, v102, v54
	v_add_f32_e32 v103, v103, v55
	v_add_f32_e32 v102, v102, v56
	v_add_f32_e32 v103, v103, v57
	v_add_f32_e32 v102, v102, v58
	v_add_f32_e32 v103, v103, v59
	v_add_f32_e32 v102, v102, v60
	v_add_f32_e32 v103, v103, v61
	v_add_f32_e32 v102, v102, v62
	v_add_f32_e32 v103, v103, v63
	v_add_f32_e32 v102, v102, v103
	v_add_f32_e32 v99, v99, v102
	ds_read_b64 v[212:213], v240 offset:0
	ds_read_b64 v[214:215], v241 offset:0
	ds_read_b64 v[216:217], v240 offset:2048
	ds_read_b64 v[218:219], v241 offset:2048
	ds_read_b64 v[220:221], v242 offset:0
	ds_read_b64 v[222:223], v243 offset:0
	ds_read_b64 v[224:225], v242 offset:2048
	ds_read_b64 v[226:227], v243 offset:2048
	v_cvt_pk_bf16_f32 v48, v48, v49
	v_cvt_pk_bf16_f32 v49, v50, v51
	v_cvt_pk_bf16_f32 v50, v52, v53
	v_cvt_pk_bf16_f32 v51, v54, v55
	v_cvt_pk_bf16_f32 v56, v56, v57
	v_cvt_pk_bf16_f32 v57, v58, v59
	v_cvt_pk_bf16_f32 v58, v60, v61
	v_cvt_pk_bf16_f32 v59, v62, v63
	s_waitcnt lgkmcnt(0)
	s_cmp_lt_u32 s77, s65
	s_cbranch_scc0 .Lat_novdma_12
	s_add_i32 m0, s70, 0x1000
	s_nop 0
	global_load_lds_dwordx4 v232, s[54:55]
	s_add_i32 m0, s70, 0x1400
	s_nop 0
	global_load_lds_dwordx4 v233, s[54:55]
	s_add_i32 m0, s70, 0x1800
	s_nop 0
	global_load_lds_dwordx4 v234, s[54:55]
	s_add_i32 m0, s70, 0x1c00
	s_nop 0
	global_load_lds_dwordx4 v235, s[54:55]
	s_add_u32 s54, s54, s84
	s_addc_u32 s55, s55, 0

; DI void attn_block(const AttnItem& it, int key0, int qi, int hh, const bf16x8 (&bq)[4], LAS unsigned char* Kl, LAS unsigned char* Vl, unsigned kr, unsigned vr,
;                    float& mrun, float& lsum, f32x16& o0, f32x16& o1) {
;     ...
;     float mx = s[0];
; #pragma unroll
;     for (int r = 1; r < 16; ++r) mx = fmaxf(mx, s[r]);
;     mx = fmaxf(mx, __shfl_xor(mx, 32));
;     const float mnew = fmaxf(mrun, mx);
;     const float alpha = __builtin_amdgcn_exp2f(mrun - mnew);
;     mrun = mnew;
;     float rs = 0.f;
; #pragma unroll
;     for (int r = 0; r < 16; ++r) { s[r] = __builtin_amdgcn_exp2f(s[r] - mnew); rs += s[r]; }
;     lsum = lsum * alpha + rs;
; #pragma unroll
;     for (int r = 0; r < 16; ++r) { o0[r] *= alpha; o1[r] *= alpha; }
.Lat_nomask_22:
	v_max3_f32 v96, v64, v65, v66
	v_max3_f32 v97, v67, v68, v69
	v_max3_f32 v96, v96, v70, v71
	v_max3_f32 v97, v97, v72, v73
	v_max3_f32 v96, v96, v74, v75
	v_max3_f32 v97, v97, v76, v77
	v_max3_f32 v96, v96, v78, v79
	v_max_f32_e32 v96, v96, v97
	v_mov_b32_e32 v97, v96
	s_nop 1
	v_permlane32_swap_b32_e32 v96, v97
	v_max_f32_e32 v96, v96, v97
	v_add_f32_e32 v96, s83, v96
	v_sub_f32_e32 v97, v96, v98
	v_cmp_lt_f32_e32 vcc, 4.0, v97
	s_cbranch_vccz .Lat_noupd_25
	v_max_f32_e32 v96, v98, v96
	v_sub_f32_e32 v100, v98, v96
	v_exp_f32_e32 v100, v100
	v_mov_b32_e32 v98, v96
	v_mul_f32_e32 v99, v99, v100
	v_mul_f32_e32 v16, v100, v16
	v_mul_f32_e32 v32, v100, v32
	v_mul_f32_e32 v17, v100, v17
	v_mul_f32_e32 v33, v100, v33
	v_mul_f32_e32 v18, v100, v18
	v_mul_f32_e32 v34, v100, v34
	v_mul_f32_e32 v19, v100, v19
	v_mul_f32_e32 v35, v100, v35
	v_mul_f32_e32 v20, v100, v20
	v_mul_f32_e32 v36, v100, v36
	v_mul_f32_e32 v21, v100, v21
	v_mul_f32_e32 v37, v100, v37
	v_mul_f32_e32 v22, v100, v22
	v_mul_f32_e32 v38, v100, v38
	v_mul_f32_e32 v23, v100, v23
	v_mul_f32_e32 v39, v100, v39
	v_mul_f32_e32 v24, v100, v24
	v_mul_f32_e32 v40, v100, v40
	v_mul_f32_e32 v25, v100, v25
	v_mul_f32_e32 v41, v100, v41
	v_mul_f32_e32 v26, v100, v26
	v_mul_f32_e32 v42, v100, v42
	v_mul_f32_e32 v27, v100, v27
	v_mul_f32_e32 v43, v100, v43
	v_mul_f32_e32 v28, v100, v28
	v_mul_f32_e32 v44, v100, v44
	v_mul_f32_e32 v29, v100, v29
	v_mul_f32_e32 v45, v100, v45
	v_mul_f32_e32 v30, v100, v30
	v_mul_f32_e32 v46, v100, v46
	v_mul_f32_e32 v31, v100, v31
	v_mul_f32_e32 v47, v100, v47
.Lat_noupd_25:
	v_sub_f32_e32 v101, s83, v98
	s_cmp_lt_u32 s79, s65
	s_cbranch_scc0 .Lat_nomfma_24
	s_waitcnt lgkmcnt(0)
	v_mfma_f32_32x32x16_bf16 v[48:63], v[80:83], v[0:3], 0
	v_mfma_f32_32x32x16_bf16 v[48:63], v[84:87], v[4:7], v[48:63]
	v_mfma_f32_32x32x16_bf16 v[48:63], v[88:91], v[8:11], v[48:63]
	v_mfma_f32_32x32x16_bf16 v[48:63], v[92:95], v[12:15], v[48:63]
.Lat_nomfma_24:
	v_add_f32_e32 v64, v101, v64
	v_add_f32_e32 v65, v101, v65
	v_add_f32_e32 v66, v101, v66
	v_add_f32_e32 v67, v101, v67
	v_add_f32_e32 v68, v101, v68
	v_add_f32_e32 v69, v101, v69
	v_add_f32_e32 v70, v101, v70
	v_add_f32_e32 v71, v101, v71
	v_add_f32_e32 v72, v101, v72
	v_add_f32_e32 v73, v101, v73
	v_add_f32_e32 v74, v101, v74
	v_add_f32_e32 v75, v101, v75
	v_add_f32_e32 v76, v101, v76
	v_add_f32_e32 v77, v101, v77
	v_add_f32_e32 v78, v101, v78
	v_add_f32_e32 v79, v101, v79
	v_exp_f32_e32 v64, v64
	v_exp_f32_e32 v65, v65
	v_exp_f32_e32 v66, v66
	v_exp_f32_e32 v67, v67
	v_exp_f32_e32 v68, v68
	v_exp_f32_e32 v69, v69
	v_exp_f32_e32 v70, v70
	v_exp_f32_e32 v71, v71
	v_exp_f32_e32 v72, v72
	v_exp_f32_e32 v73, v73
	v_exp_f32_e32 v74, v74
	v_exp_f32_e32 v75, v75
	v_exp_f32_e32 v76, v76
	v_exp_f32_e32 v77, v77
	v_exp_f32_e32 v78, v78
	v_exp_f32_e32 v79, v79
	v_add_f32_e32 v102, v64, v65
	v_add_f32_e32 v103, v66, v67
	v_add_f32_e32 v102, v102, v68
	v_add_f32_e32 v103, v103, v69
	v_add_f32_e32 v102, v102, v70
	v_add_f32_e32 v103, v103, v71
	v_add_f32_e32 v102, v102, v72
	v_add_f32_e32 v103, v103, v73
	v_add_f32_e32 v102, v102, v74
	v_add_f32_e32 v103, v103, v75
	v_add_f32_e32 v102, v102, v76
	v_add_f32_e32 v103, v103, v77
	v_add_f32_e32 v102, v102, v78
	v_add_f32_e32 v103, v103, v79
	v_add_f32_e32 v102, v102, v103
	v_add_f32_e32 v99, v99, v102
	ds_read_b64 v[212:213], v240 offset:8192
	ds_read_b64 v[214:215], v241 offset:8192
	ds_read_b64 v[216:217], v240 offset:10240
	ds_read_b64 v[218:219], v241 offset:10240
	ds_read_b64 v[220:221], v242 offset:8192
	ds_read_b64 v[222:223], v243 offset:8192
	ds_read_b64 v[224:225], v242 offset:10240
	ds_read_b64 v[226:227], v243 offset:10240
	v_cvt_pk_bf16_f32 v64, v64, v65
	v_cvt_pk_bf16_f32 v65, v66, v67
	v_cvt_pk_bf16_f32 v66, v68, v69
	v_cvt_pk_bf16_f32 v67, v70, v71
	v_cvt_pk_bf16_f32 v72, v72, v73
	v_cvt_pk_bf16_f32 v73, v74, v75
	v_cvt_pk_bf16_f32 v74, v76, v77
	v_cvt_pk_bf16_f32 v75, v78, v79
	s_waitcnt lgkmcnt(0)
	s_cmp_lt_u32 s77, s65
	s_cbranch_scc0 .Lat_novdma_23
	s_add_i32 m0, s70, 0x3000
	s_nop 0
	global_load_lds_dwordx4 v232, s[54:55]
	s_add_i32 m0, s70, 0x3400
	s_nop 0
	global_load_lds_dwordx4 v233, s[54:55]
	s_add_i32 m0, s70, 0x3800
	s_nop 0
	global_load_lds_dwordx4 v234, s[54:55]
	s_add_i32 m0, s70, 0x3c00
	s_nop 0
	global_load_lds_dwordx4 v235, s[54:55]
	s_add_u32 s54, s54, s84
	s_addc_u32 s55, s55, 0

; DI void attn_block(const AttnItem& it, int key0, int qi, int hh, const bf16x8 (&bq)[4], LAS unsigned char* Kl, LAS unsigned char* Vl, unsigned kr, unsigned vr,
;                    float& mrun, float& lsum, f32x16& o0, f32x16& o1) {
;     ...
;     float mx = s[0];
; #pragma unroll
;     for (int r = 1; r < 16; ++r) mx = fmaxf(mx, s[r]);
;     mx = fmaxf(mx, __shfl_xor(mx, 32));
;     const float mnew = fmaxf(mrun, mx);
;     const float alpha = __builtin_amdgcn_exp2f(mrun - mnew);
;     mrun = mnew;
;     float rs = 0.f;
; #pragma unroll
;     for (int r = 0; r < 16; ++r) { s[r] = __builtin_amdgcn_exp2f(s[r] - mnew); rs += s[r]; }
;     lsum = lsum * alpha + rs;
; #pragma unroll
;     for (int r = 0; r < 16; ++r) { o0[r] *= alpha; o1[r] *= alpha; }
.Lat_bdone_2009:
	v_max3_f32 v196, v212, v213, v214
	v_max3_f32 v197, v215, v216, v217
	v_max3_f32 v196, v196, v218, v219
	v_max3_f32 v197, v197, v220, v221
	v_max3_f32 v196, v196, v222, v223
	v_max3_f32 v197, v197, v224, v225
	v_max3_f32 v196, v196, v226, v227
	v_max_f32_e32 v196, v196, v197
	v_mov_b32_e32 v197, v196
	s_nop 1
	v_permlane32_swap_b32_e32 v196, v197
	v_max_f32_e32 v196, v196, v197
	v_add_f32_e32 v196, s83, v196
	v_sub_f32_e32 v197, v196, v150
	v_cmp_lt_f32_e32 vcc, 4.0, v197
	s_cbranch_vccz .Lat_noupd_2010
	v_max_f32_e32 v196, v150, v196
	v_sub_f32_e32 v198, v150, v196
	v_exp_f32_e32 v198, v198
	v_mov_b32_e32 v150, v196
	v_mul_f32_e32 v152, v152, v198
	v_mul_f32_e32 v32, v198, v32
	v_mul_f32_e32 v48, v198, v48
	v_mul_f32_e32 v33, v198, v33
	v_mul_f32_e32 v49, v198, v49
	v_mul_f32_e32 v34, v198, v34
	v_mul_f32_e32 v50, v198, v50
	v_mul_f32_e32 v35, v198, v35
	v_mul_f32_e32 v51, v198, v51
	v_mul_f32_e32 v36, v198, v36
	v_mul_f32_e32 v52, v198, v52
	v_mul_f32_e32 v37, v198, v37
	v_mul_f32_e32 v53, v198, v53
	v_mul_f32_e32 v38, v198, v38
	v_mul_f32_e32 v54, v198, v54
	v_mul_f32_e32 v39, v198, v39
	v_mul_f32_e32 v55, v198, v55
	v_mul_f32_e32 v40, v198, v40
	v_mul_f32_e32 v56, v198, v56
	v_mul_f32_e32 v41, v198, v41
	v_mul_f32_e32 v57, v198, v57
	v_mul_f32_e32 v42, v198, v42
	v_mul_f32_e32 v58, v198, v58
	v_mul_f32_e32 v43, v198, v43
	v_mul_f32_e32 v59, v198, v59
	v_mul_f32_e32 v44, v198, v44
	v_mul_f32_e32 v60, v198, v60
	v_mul_f32_e32 v45, v198, v45
	v_mul_f32_e32 v61, v198, v61
	v_mul_f32_e32 v46, v198, v46
	v_mul_f32_e32 v62, v198, v62
	v_mul_f32_e32 v47, v198, v47
	v_mul_f32_e32 v63, v198, v63
.Lat_noupd_2010:
	v_sub_f32_e32 v199, s83, v150
	v_add_f32_e32 v212, v199, v212
	v_add_f32_e32 v213, v199, v213
	v_add_f32_e32 v214, v199, v214
	v_add_f32_e32 v215, v199, v215
	v_add_f32_e32 v216, v199, v216
	v_add_f32_e32 v217, v199, v217
	v_add_f32_e32 v218, v199, v218
	v_add_f32_e32 v219, v199, v219
	v_add_f32_e32 v220, v199, v220
	v_add_f32_e32 v221, v199, v221
	v_add_f32_e32 v222, v199, v222
	v_add_f32_e32 v223, v199, v223
	v_add_f32_e32 v224, v199, v224
	v_add_f32_e32 v225, v199, v225
	v_add_f32_e32 v226, v199, v226
	v_add_f32_e32 v227, v199, v227
	v_exp_f32_e32 v212, v212
	v_exp_f32_e32 v213, v213
	v_exp_f32_e32 v214, v214
	v_exp_f32_e32 v215, v215
	v_exp_f32_e32 v216, v216
	v_exp_f32_e32 v217, v217
	v_exp_f32_e32 v218, v218
	v_exp_f32_e32 v219, v219
	v_exp_f32_e32 v220, v220
	v_exp_f32_e32 v221, v221
	v_exp_f32_e32 v222, v222
	v_exp_f32_e32 v223, v223
	v_exp_f32_e32 v224, v224
	v_exp_f32_e32 v225, v225
	v_exp_f32_e32 v226, v226
	v_exp_f32_e32 v227, v227
	v_add_f32_e32 v200, v212, v213
	v_add_f32_e32 v201, v214, v215
	v_add_f32_e32 v200, v200, v216
	v_add_f32_e32 v201, v201, v217
	v_add_f32_e32 v200, v200, v218
	v_add_f32_e32 v201, v201, v219
	v_add_f32_e32 v200, v200, v220
	v_add_f32_e32 v201, v201, v221
	v_add_f32_e32 v200, v200, v222
	v_add_f32_e32 v201, v201, v223
	v_add_f32_e32 v200, v200, v224
	v_add_f32_e32 v201, v201, v225
	v_add_f32_e32 v200, v200, v226
	v_add_f32_e32 v201, v201, v227
	v_add_f32_e32 v200, v200, v201
	v_add_f32_e32 v152, v152, v200
	v_cvt_pk_bf16_f32 v212, v212, v213
	v_cvt_pk_bf16_f32 v213, v214, v215
	v_cvt_pk_bf16_f32 v214, v216, v217
	v_cvt_pk_bf16_f32 v215, v218, v219
	v_cvt_pk_bf16_f32 v220, v220, v221
	v_cvt_pk_bf16_f32 v221, v222, v223
	v_cvt_pk_bf16_f32 v222, v224, v225
	v_cvt_pk_bf16_f32 v223, v226, v227
	s_cmp_lt_u32 s77, s65
	s_cbranch_scc1 .Lat_v12_2004
	s_cmp_lt_u32 s79, s65
	s_cbranch_scc1 .Lat_v8_2005
	s_waitcnt vmcnt(0)
	s_branch .Lat_vdone_2006

; #define LAS __attribute__((address_space(3)))
; DI unsigned pk2(float a, float b) { f32x2 v = {a, b}; bf2v r = __builtin_convertvector(v, bf2v); return __builtin_bit_cast(unsigned, r); }
; #define MFMA32(a, b, c) __builtin_amdgcn_mfma_f32_32x32x16_bf16((a), (b), (c), 0, 0, 0)
; DI void attn_block(const AttnItem& it, int key0, int qi, int hh, const bf16x8 (&bq)[4], LAS unsigned char* Kl, LAS unsigned char* Vl, unsigned kr, unsigned vr,
;                    float& mrun, float& lsum, f32x16& o0, f32x16& o1) {
;     ...
;     float mx = s[0];
; #pragma unroll
;     for (int r = 1; r < 16; ++r) mx = fmaxf(mx, s[r]);
;     mx = fmaxf(mx, __shfl_xor(mx, 32));
;     const float mnew = fmaxf(mrun, mx);
;     const float alpha = __builtin_amdgcn_exp2f(mrun - mnew);
;     mrun = mnew;
;     float rs = 0.f;
; #pragma unroll
;     for (int r = 0; r < 16; ++r) { s[r] = __builtin_amdgcn_exp2f(s[r] - mnew); rs += s[r]; }
;     lsum = lsum * alpha + rs;
; #pragma unroll
;     for (int r = 0; r < 16; ++r) { o0[r] *= alpha; o1[r] *= alpha; }
; #pragma unroll
;     for (int ks = 0; ks < 2; ++ks) {
;         u32x4 pw; pw.x = pk2(s[8 * ks], s[8 * ks + 1]); pw.y = pk2(s[8 * ks + 2], s[8 * ks + 3]); pw.z = pk2(s[8 * ks + 4], s[8 * ks + 5]); pw.w = pk2(s[8 * ks + 6], s[8 * ks + 7]);
;         const bf16x8 pb = __builtin_bit_cast(bf16x8, pw);
;         const u32x2 a00 = *(const LAS u32x2*)(Vl + vr + ks * 32), a01 = *(const LAS u32x2*)(Vl + vr + ks * 32 + 16);
;         const u32x2 a10 = *(const LAS u32x2*)(Vl + vr + 2560 + ks * 32), a11 = *(const LAS u32x2*)(Vl + vr + 2560 + ks * 32 + 16);
;         u32x4 a0; a0.x = a00.x; a0.y = a00.y; a0.z = a01.x; a0.w = a01.y;
;         u32x4 a1; a1.x = a10.x; a1.y = a10.y; a1.z = a11.x; a1.w = a11.y;
;         o0 = MFMA32(__builtin_bit_cast(bf16x8, a0), pb, o0);
;         o1 = MFMA32(__builtin_bit_cast(bf16x8, a1), pb, o1);
;     }
.Lat_bdone_2012:
	v_max3_f32 v196, v228, v229, v230
	v_max3_f32 v197, v231, v232, v233
	v_max3_f32 v196, v196, v234, v235
	v_max3_f32 v197, v197, v236, v237
	v_max3_f32 v196, v196, v238, v239
	v_max3_f32 v197, v197, v240, v241
	v_max3_f32 v196, v196, v242, v243
	v_max_f32_e32 v196, v196, v197
	v_mov_b32_e32 v197, v196
	s_nop 1
	v_permlane32_swap_b32_e32 v196, v197
	v_max_f32_e32 v196, v196, v197
	v_add_f32_e32 v196, s83, v196
	v_sub_f32_e32 v197, v196, v151
	v_cmp_lt_f32_e32 vcc, 4.0, v197
	s_cbranch_vccz .Lat_noupd_2013
	v_max_f32_e32 v196, v151, v196
	v_sub_f32_e32 v198, v151, v196
	v_exp_f32_e32 v198, v198
	v_mov_b32_e32 v151, v196
	v_mul_f32_e32 v157, v157, v198
	v_mul_f32_e32 v64, v198, v64
	v_mul_f32_e32 v80, v198, v80
	v_mul_f32_e32 v65, v198, v65
	v_mul_f32_e32 v81, v198, v81
	v_mul_f32_e32 v66, v198, v66
	v_mul_f32_e32 v82, v198, v82
	v_mul_f32_e32 v67, v198, v67
	v_mul_f32_e32 v83, v198, v83
	v_mul_f32_e32 v68, v198, v68
	v_mul_f32_e32 v84, v198, v84
	v_mul_f32_e32 v69, v198, v69
	v_mul_f32_e32 v85, v198, v85
	v_mul_f32_e32 v70, v198, v70
	v_mul_f32_e32 v86, v198, v86
	v_mul_f32_e32 v71, v198, v71
	v_mul_f32_e32 v87, v198, v87
	v_mul_f32_e32 v72, v198, v72
	v_mul_f32_e32 v88, v198, v88
	v_mul_f32_e32 v73, v198, v73
	v_mul_f32_e32 v89, v198, v89
	v_mul_f32_e32 v74, v198, v74
	v_mul_f32_e32 v90, v198, v90
	v_mul_f32_e32 v75, v198, v75
	v_mul_f32_e32 v91, v198, v91
	v_mul_f32_e32 v76, v198, v76
	v_mul_f32_e32 v92, v198, v92
	v_mul_f32_e32 v77, v198, v77
	v_mul_f32_e32 v93, v198, v93
	v_mul_f32_e32 v78, v198, v78
	v_mul_f32_e32 v94, v198, v94
	v_mul_f32_e32 v79, v198, v79
	v_mul_f32_e32 v95, v198, v95
.Lat_noupd_2013:
	v_sub_f32_e32 v199, s83, v151
	v_add_f32_e32 v228, v199, v228
	v_add_f32_e32 v229, v199, v229
	v_add_f32_e32 v230, v199, v230
	v_add_f32_e32 v231, v199, v231
	v_add_f32_e32 v232, v199, v232
	v_add_f32_e32 v233, v199, v233
	v_add_f32_e32 v234, v199, v234
	v_add_f32_e32 v235, v199, v235
	v_add_f32_e32 v236, v199, v236
	v_add_f32_e32 v237, v199, v237
	v_add_f32_e32 v238, v199, v238
	v_add_f32_e32 v239, v199, v239
	v_add_f32_e32 v240, v199, v240
	v_add_f32_e32 v241, v199, v241
	v_add_f32_e32 v242, v199, v242
	v_add_f32_e32 v243, v199, v243
	v_exp_f32_e32 v228, v228
	v_exp_f32_e32 v229, v229
	v_exp_f32_e32 v230, v230
	v_exp_f32_e32 v231, v231
	v_exp_f32_e32 v232, v232
	v_exp_f32_e32 v233, v233
	v_exp_f32_e32 v234, v234
	v_exp_f32_e32 v235, v235
	v_exp_f32_e32 v236, v236
	v_exp_f32_e32 v237, v237
	v_exp_f32_e32 v238, v238
	v_exp_f32_e32 v239, v239
	v_exp_f32_e32 v240, v240
	v_exp_f32_e32 v241, v241
	v_exp_f32_e32 v242, v242
	v_exp_f32_e32 v243, v243
	v_add_f32_e32 v200, v228, v229
	v_add_f32_e32 v201, v230, v231
	v_add_f32_e32 v200, v200, v232
	v_add_f32_e32 v201, v201, v233
	v_add_f32_e32 v200, v200, v234
	v_add_f32_e32 v201, v201, v235
	v_add_f32_e32 v200, v200, v236
	v_add_f32_e32 v201, v201, v237
	v_add_f32_e32 v200, v200, v238
	v_add_f32_e32 v201, v201, v239
	v_add_f32_e32 v200, v200, v240
	v_add_f32_e32 v201, v201, v241
	v_add_f32_e32 v200, v200, v242
	v_add_f32_e32 v201, v201, v243
	v_add_f32_e32 v200, v200, v201
	v_add_f32_e32 v157, v157, v200
	v_cvt_pk_bf16_f32 v228, v228, v229
	v_cvt_pk_bf16_f32 v229, v230, v231
	v_cvt_pk_bf16_f32 v230, v232, v233
	v_cvt_pk_bf16_f32 v231, v234, v235
	v_cvt_pk_bf16_f32 v236, v236, v237
	v_cvt_pk_bf16_f32 v237, v238, v239
	v_cvt_pk_bf16_f32 v238, v240, v241
	v_cvt_pk_bf16_f32 v239, v242, v243
	s_nop 1
	v_mfma_f32_32x32x16_bf16 v[64:79], v[120:123], v[228:231], v[64:79]
	v_mfma_f32_32x32x16_bf16 v[80:95], v[124:127], v[228:231], v[80:95]
	v_mfma_f32_32x32x16_bf16 v[64:79], v[158:161], v[236:239], v[64:79]
	v_mfma_f32_32x32x16_bf16 v[80:95], v[162:165], v[236:239], v[80:95]
	s_add_i32 s71, s71, 1
	s_sub_i32 s66, s66, 32
	s_add_i32 s79, s71, 1
	s_add_i32 s77, s71, 2
	s_cmp_lt_u32 s79, s65
	s_cbranch_scc1 .Lat_k12_2014
	s_waitcnt vmcnt(4)
	s_branch .Lat_kdone_2015

; #define LAS __attribute__((address_space(3)))
; DI float bflo(unsigned w) { return __uint_as_float(w << 16); }
; DI void attn_block(const AttnItem& it, int key0, int qi, int hh, const bf16x8 (&bq)[4], LAS unsigned char* Kl, LAS unsigned char* Vl, unsigned kr, unsigned vr,
;                    float& mrun, float& lsum, f32x16& o0, f32x16& o1) {
;     ...
;     float mx = s[0];
; #pragma unroll
;     for (int r = 1; r < 16; ++r) mx = fmaxf(mx, s[r]);
;     mx = fmaxf(mx, __shfl_xor(mx, 32));
;     const float mnew = fmaxf(mrun, mx);
;     const float alpha = __builtin_amdgcn_exp2f(mrun - mnew);
;     mrun = mnew;
;     float rs = 0.f;
; #pragma unroll
;     for (int r = 0; r < 16; ++r) { s[r] = __builtin_amdgcn_exp2f(s[r] - mnew); rs += s[r]; }
;     lsum = lsum * alpha + rs;
; #pragma unroll
;     for (int r = 0; r < 16; ++r) { o0[r] *= alpha; o1[r] *= alpha; }
; #pragma unroll
;     for (int ks = 0; ks < 2; ++ks) {
;         u32x4 pw; pw.x = pk2(s[8 * ks], s[8 * ks + 1]); pw.y = pk2(s[8 * ks + 2], s[8 * ks + 3]); pw.z = pk2(s[8 * ks + 4], s[8 * ks + 5]); pw.w = pk2(s[8 * ks + 6], s[8 * ks + 7]);
;         const bf16x8 pb = __builtin_bit_cast(bf16x8, pw);
;         const u32x2 a00 = *(const LAS u32x2*)(Vl + vr + ks * 32), a01 = *(const LAS u32x2*)(Vl + vr + ks * 32 + 16);
;         const u32x2 a10 = *(const LAS u32x2*)(Vl + vr + 2560 + ks * 32), a11 = *(const LAS u32x2*)(Vl + vr + 2560 + ks * 32 + 16);
;         u32x4 a0; a0.x = a00.x; a0.y = a00.y; a0.z = a01.x; a0.w = a01.y;
;         u32x4 a1; a1.x = a10.x; a1.y = a10.y; a1.z = a11.x; a1.w = a11.y;
;         o0 = MFMA32(__builtin_bit_cast(bf16x8, a0), pb, o0);
;         o1 = MFMA32(__builtin_bit_cast(bf16x8, a1), pb, o1);
;     }
; DI void attn_item(const AttnItem& it, LAS unsigned char* wl, int lane) {
;     ...
;     lsum += __shfl_xor(lsum, 32);
;     const float inv = __fdividef(1.f, lsum);
;     if (qi < it.nq) {
;         bf16_t* zr = it.zo + (size_t)qi * it.zold + 4 * hh;
; #pragma unroll
;         for (int g = 0; g < 4; ++g) {
;             { const u32x2 z = *(const u32x2*)(zr + 8 * g); u32x2 w;
;               w.x = pk2(o0[4 * g] * inv * bflo(z.x), o0[4 * g + 1] * inv * bfhi(z.x)); w.y = pk2(o0[4 * g + 2] * inv * bflo(z.y), o0[4 * g + 3] * inv * bfhi(z.y));
;               *(u32x2*)(zr + 8 * g) = w; }
;             { const u32x2 z = *(const u32x2*)(zr + 32 + 8 * g); u32x2 w;
.Lat_noupd_2026:
	v_sub_f32_e32 v199, s83, v151
	v_add_f32_e32 v228, v199, v228
	v_add_f32_e32 v229, v199, v229
	v_add_f32_e32 v230, v199, v230
	v_add_f32_e32 v231, v199, v231
	v_add_f32_e32 v232, v199, v232
	v_add_f32_e32 v233, v199, v233
	v_add_f32_e32 v234, v199, v234
	v_add_f32_e32 v235, v199, v235
	v_add_f32_e32 v236, v199, v236
	v_add_f32_e32 v237, v199, v237
	v_add_f32_e32 v238, v199, v238
	v_add_f32_e32 v239, v199, v239
	v_add_f32_e32 v240, v199, v240
	v_add_f32_e32 v241, v199, v241
	v_add_f32_e32 v242, v199, v242
	v_add_f32_e32 v243, v199, v243
	v_exp_f32_e32 v228, v228
	v_exp_f32_e32 v229, v229
	v_exp_f32_e32 v230, v230
	v_exp_f32_e32 v231, v231
	v_exp_f32_e32 v232, v232
	v_exp_f32_e32 v233, v233
	v_exp_f32_e32 v234, v234
	v_exp_f32_e32 v235, v235
	v_exp_f32_e32 v236, v236
	v_exp_f32_e32 v237, v237
	v_exp_f32_e32 v238, v238
	v_exp_f32_e32 v239, v239
	v_exp_f32_e32 v240, v240
	v_exp_f32_e32 v241, v241
	v_exp_f32_e32 v242, v242
	v_exp_f32_e32 v243, v243
	v_add_f32_e32 v200, v228, v229
	v_add_f32_e32 v201, v230, v231
	v_add_f32_e32 v200, v200, v232
	v_add_f32_e32 v201, v201, v233
	v_add_f32_e32 v200, v200, v234
	v_add_f32_e32 v201, v201, v235
	v_add_f32_e32 v200, v200, v236
	v_add_f32_e32 v201, v201, v237
	v_add_f32_e32 v200, v200, v238
	v_add_f32_e32 v201, v201, v239
	v_add_f32_e32 v200, v200, v240
	v_add_f32_e32 v201, v201, v241
	v_add_f32_e32 v200, v200, v242
	v_add_f32_e32 v201, v201, v243
	v_add_f32_e32 v200, v200, v201
	v_add_f32_e32 v157, v157, v200
	v_cvt_pk_bf16_f32 v228, v228, v229
	v_cvt_pk_bf16_f32 v229, v230, v231
	v_cvt_pk_bf16_f32 v230, v232, v233
	v_cvt_pk_bf16_f32 v231, v234, v235
	v_cvt_pk_bf16_f32 v236, v236, v237
	v_cvt_pk_bf16_f32 v237, v238, v239
	v_cvt_pk_bf16_f32 v238, v240, v241
	v_cvt_pk_bf16_f32 v239, v242, v243
	s_nop 1
	v_mfma_f32_32x32x16_bf16 v[64:79], v[120:123], v[228:231], v[64:79]
	v_mfma_f32_32x32x16_bf16 v[80:95], v[124:127], v[228:231], v[80:95]
	v_mfma_f32_32x32x16_bf16 v[64:79], v[158:161], v[236:239], v[64:79]
	v_mfma_f32_32x32x16_bf16 v[80:95], v[162:165], v[236:239], v[80:95]
	s_add_i32 s71, s71, 1
	s_sub_i32 s66, s66, 32
	s_cmp_lt_u32 s71, s65
	s_cbranch_scc1 .Lat2_loop
	s_nop 7
	v_mov_b32_e32 v197, v152
	s_nop 1
	v_permlane32_swap_b32_e32 v152, v197
	v_add_f32_e32 v152, v152, v197
	v_rcp_f32_e32 v152, v152
	v_mov_b32_e32 v197, v157
	s_nop 1
	v_permlane32_swap_b32_e32 v157, v197
	v_add_f32_e32 v157, v157, v197
	v_rcp_f32_e32 v157, v157
	global_load_dwordx2 v[212:213], v168, s[56:57]
	global_load_dwordx2 v[214:215], v168, s[56:57] offset:16
	global_load_dwordx2 v[216:217], v168, s[56:57] offset:32
	global_load_dwordx2 v[218:219], v168, s[56:57] offset:48
	global_load_dwordx2 v[220:221], v168, s[56:57] offset:64
	global_load_dwordx2 v[222:223], v168, s[56:57] offset:80
	global_load_dwordx2 v[224:225], v168, s[56:57] offset:96
	global_load_dwordx2 v[226:227], v168, s[56:57] offset:112
	v_add_u32_e32 v168, 0x8000, v168
	global_load_dwordx2 v[228:229], v168, s[56:57]
	global_load_dwordx2 v[230:231], v168, s[56:57] offset:16
	global_load_dwordx2 v[232:233], v168, s[56:57] offset:32
	global_load_dwordx2 v[234:235], v168, s[56:57] offset:48
	global_load_dwordx2 v[236:237], v168, s[56:57] offset:64
	global_load_dwordx2 v[238:239], v168, s[56:57] offset:80
	global_load_dwordx2 v[240:241], v168, s[56:57] offset:96
	global_load_dwordx2 v[242:243], v168, s[56:57] offset:112
	v_subrev_u32_e32 v168, 0x8000, v168
	s_waitcnt vmcnt(15)
	v_mul_f32_e32 v32, v32, v152
	v_mul_f32_e32 v33, v33, v152
	v_mul_f32_e32 v34, v34, v152
	v_mul_f32_e32 v35, v35, v152
	v_lshlrev_b32_e32 v196, 16, v212
	v_and_b32_e32 v197, 0xffff0000, v212
	v_lshlrev_b32_e32 v198, 16, v213
	v_and_b32_e32 v199, 0xffff0000, v213
	v_mul_f32_e32 v32, v32, v196
	v_mul_f32_e32 v33, v33, v197
	v_mul_f32_e32 v34, v34, v198
	v_mul_f32_e32 v35, v35, v199
	v_cvt_pk_bf16_f32 v32, v32, v33
	v_cvt_pk_bf16_f32 v33, v34, v35
	global_store_dwordx2 v168, v[32:33], s[56:57]
	s_waitcnt vmcnt(15)
	v_mul_f32_e32 v36, v36, v152
	v_mul_f32_e32 v37, v37, v152
	v_mul_f32_e32 v38, v38, v152
	v_mul_f32_e32 v39, v39, v152
	v_lshlrev_b32_e32 v196, 16, v214
	v_and_b32_e32 v197, 0xffff0000, v214
	v_lshlrev_b32_e32 v198, 16, v215
	v_and_b32_e32 v199, 0xffff0000, v215
	v_mul_f32_e32 v36, v36, v196
	v_mul_f32_e32 v37, v37, v197
	v_mul_f32_e32 v38, v38, v198
	v_mul_f32_e32 v39, v39, v199
	v_cvt_pk_bf16_f32 v36, v36, v37
	v_cvt_pk_bf16_f32 v37, v38, v39
	global_store_dwordx2 v168, v[36:37], s[56:57] offset:16
	s_waitcnt vmcnt(15)
	v_mul_f32_e32 v40, v40, v152
	v_mul_f32_e32 v41, v41, v152
	v_mul_f32_e32 v42, v42, v152
	v_mul_f32_e32 v43, v43, v152
	v_lshlrev_b32_e32 v196, 16, v216
	v_and_b32_e32 v197, 0xffff0000, v216
	v_lshlrev_b32_e32 v198, 16, v217
	v_and_b32_e32 v199, 0xffff0000, v217
	v_mul_f32_e32 v40, v40, v196
	v_mul_f32_e32 v41, v41, v197
	v_mul_f32_e32 v42, v42, v198
	v_mul_f32_e32 v43, v43, v199
	v_cvt_pk_bf16_f32 v40, v40, v41
	v_cvt_pk_bf16_f32 v41, v42, v43
	global_store_dwordx2 v168, v[40:41], s[56:57] offset:32
	s_waitcnt vmcnt(15)
	v_mul_f32_e32 v44, v44, v152
	v_mul_f32_e32 v45, v45, v152
	v_mul_f32_e32 v46, v46, v152
	v_mul_f32_e32 v47, v47, v152
	v_lshlrev_b32_e32 v196, 16, v218
	v_and_b32_e32 v197, 0xffff0000, v218
	v_lshlrev_b32_e32 v198, 16, v219
	v_and_b32_e32 v199, 0xffff0000, v219
	v_mul_f32_e32 v44, v44, v196
	v_mul_f32_e32 v45, v45, v197
	v_mul_f32_e32 v46, v46, v198
	v_mul_f32_e32 v47, v47, v199
	v_cvt_pk_bf16_f32 v44, v44, v45
	v_cvt_pk_bf16_f32 v45, v46, v47
	global_store_dwordx2 v168, v[44:45], s[56:57] offset:48
	s_waitcnt vmcnt(15)
; DI unsigned pk2(float a, float b) { f32x2 v = {a, b}; bf2v r = __builtin_convertvector(v, bf2v); return __builtin_bit_cast(unsigned, r); }
; DI float bflo(unsigned w) { return __uint_as_float(w << 16); }
; DI float bfhi(unsigned w) { return __uint_as_float(w & 0xffff0000u); }
; DI void attn_item(const AttnItem& it, LAS unsigned char* wl, int lane) {
;     ...
;     if (qi < it.nq) {
;         bf16_t* zr = it.zo + (size_t)qi * it.zold + 4 * hh;
; #pragma unroll
;         for (int g = 0; g < 4; ++g) {
;             { const u32x2 z = *(const u32x2*)(zr + 8 * g); u32x2 w;
;               w.x = pk2(o0[4 * g] * inv * bflo(z.x), o0[4 * g + 1] * inv * bfhi(z.x)); w.y = pk2(o0[4 * g + 2] * inv * bflo(z.y), o0[4 * g + 3] * inv * bfhi(z.y));
;               *(u32x2*)(zr + 8 * g) = w; }
;             { const u32x2 z = *(const u32x2*)(zr + 32 + 8 * g); u32x2 w;
;               w.x = pk2(o1[4 * g] * inv * bflo(z.x), o1[4 * g + 1] * inv * bfhi(z.x)); w.y = pk2(o1[4 * g + 2] * inv * bflo(z.y), o1[4 * g + 3] * inv * bfhi(z.y));
;               *(u32x2*)(zr + 32 + 8 * g) = w; }
;         }
	v_mul_f32_e32 v48, v48, v152
	v_mul_f32_e32 v49, v49, v152
	v_mul_f32_e32 v50, v50, v152
	v_mul_f32_e32 v51, v51, v152
	v_lshlrev_b32_e32 v196, 16, v220
	v_and_b32_e32 v197, 0xffff0000, v220
	v_lshlrev_b32_e32 v198, 16, v221
	v_and_b32_e32 v199, 0xffff0000, v221
	v_mul_f32_e32 v48, v48, v196
	v_mul_f32_e32 v49, v49, v197
	v_mul_f32_e32 v50, v50, v198
	v_mul_f32_e32 v51, v51, v199
	v_cvt_pk_bf16_f32 v48, v48, v49
	v_cvt_pk_bf16_f32 v49, v50, v51
	global_store_dwordx2 v168, v[48:49], s[56:57] offset:64
	s_waitcnt vmcnt(15)
	v_mul_f32_e32 v52, v52, v152
	v_mul_f32_e32 v53, v53, v152
	v_mul_f32_e32 v54, v54, v152
	v_mul_f32_e32 v55, v55, v152
	v_lshlrev_b32_e32 v196, 16, v222
	v_and_b32_e32 v197, 0xffff0000, v222
	v_lshlrev_b32_e32 v198, 16, v223
	v_and_b32_e32 v199, 0xffff0000, v223
	v_mul_f32_e32 v52, v52, v196
	v_mul_f32_e32 v53, v53, v197
	v_mul_f32_e32 v54, v54, v198
	v_mul_f32_e32 v55, v55, v199
	v_cvt_pk_bf16_f32 v52, v52, v53
	v_cvt_pk_bf16_f32 v53, v54, v55
	global_store_dwordx2 v168, v[52:53], s[56:57] offset:80
	s_waitcnt vmcnt(15)
	v_mul_f32_e32 v56, v56, v152
	v_mul_f32_e32 v57, v57, v152
	v_mul_f32_e32 v58, v58, v152
	v_mul_f32_e32 v59, v59, v152
	v_lshlrev_b32_e32 v196, 16, v224
	v_and_b32_e32 v197, 0xffff0000, v224
	v_lshlrev_b32_e32 v198, 16, v225
	v_and_b32_e32 v199, 0xffff0000, v225
	v_mul_f32_e32 v56, v56, v196
	v_mul_f32_e32 v57, v57, v197
	v_mul_f32_e32 v58, v58, v198
	v_mul_f32_e32 v59, v59, v199
	v_cvt_pk_bf16_f32 v56, v56, v57
	v_cvt_pk_bf16_f32 v57, v58, v59
	global_store_dwordx2 v168, v[56:57], s[56:57] offset:96
	s_waitcnt vmcnt(15)
	v_mul_f32_e32 v60, v60, v152
	v_mul_f32_e32 v61, v61, v152
	v_mul_f32_e32 v62, v62, v152
	v_mul_f32_e32 v63, v63, v152
	v_lshlrev_b32_e32 v196, 16, v226
	v_and_b32_e32 v197, 0xffff0000, v226
	v_lshlrev_b32_e32 v198, 16, v227
	v_and_b32_e32 v199, 0xffff0000, v227
	v_mul_f32_e32 v60, v60, v196
	v_mul_f32_e32 v61, v61, v197
	v_mul_f32_e32 v62, v62, v198
	v_mul_f32_e32 v63, v63, v199
	v_cvt_pk_bf16_f32 v60, v60, v61
	v_cvt_pk_bf16_f32 v61, v62, v63
	global_store_dwordx2 v168, v[60:61], s[56:57] offset:112
	v_add_u32_e32 v168, 0x8000, v168
	s_waitcnt vmcnt(15)
	v_mul_f32_e32 v64, v64, v157
	v_mul_f32_e32 v65, v65, v157
	v_mul_f32_e32 v66, v66, v157
	v_mul_f32_e32 v67, v67, v157
	v_lshlrev_b32_e32 v196, 16, v228
	v_and_b32_e32 v197, 0xffff0000, v228
	v_lshlrev_b32_e32 v198, 16, v229
	v_and_b32_e32 v199, 0xffff0000, v229
	v_mul_f32_e32 v64, v64, v196
	v_mul_f32_e32 v65, v65, v197
	v_mul_f32_e32 v66, v66, v198
	v_mul_f32_e32 v67, v67, v199
	v_cvt_pk_bf16_f32 v64, v64, v65
	v_cvt_pk_bf16_f32 v65, v66, v67
	global_store_dwordx2 v168, v[64:65], s[56:57]
	s_waitcnt vmcnt(15)
	v_mul_f32_e32 v68, v68, v157
	v_mul_f32_e32 v69, v69, v157
	v_mul_f32_e32 v70, v70, v157
	v_mul_f32_e32 v71, v71, v157
	v_lshlrev_b32_e32 v196, 16, v230
	v_and_b32_e32 v197, 0xffff0000, v230
	v_lshlrev_b32_e32 v198, 16, v231
	v_and_b32_e32 v199, 0xffff0000, v231
	v_mul_f32_e32 v68, v68, v196
	v_mul_f32_e32 v69, v69, v197
	v_mul_f32_e32 v70, v70, v198
	v_mul_f32_e32 v71, v71, v199
	v_cvt_pk_bf16_f32 v68, v68, v69
	v_cvt_pk_bf16_f32 v69, v70, v71
	global_store_dwordx2 v168, v[68:69], s[56:57] offset:16
	s_waitcnt vmcnt(15)
	v_mul_f32_e32 v72, v72, v157
	v_mul_f32_e32 v73, v73, v157
	v_mul_f32_e32 v74, v74, v157
	v_mul_f32_e32 v75, v75, v157
	v_lshlrev_b32_e32 v196, 16, v232
	v_and_b32_e32 v197, 0xffff0000, v232
	v_lshlrev_b32_e32 v198, 16, v233
	v_and_b32_e32 v199, 0xffff0000, v233
	v_mul_f32_e32 v72, v72, v196
	v_mul_f32_e32 v73, v73, v197
	v_mul_f32_e32 v74, v74, v198
	v_mul_f32_e32 v75, v75, v199
	v_cvt_pk_bf16_f32 v72, v72, v73
	v_cvt_pk_bf16_f32 v73, v74, v75
	global_store_dwordx2 v168, v[72:73], s[56:57] offset:32
	s_waitcnt vmcnt(15)
	v_mul_f32_e32 v76, v76, v157
	v_mul_f32_e32 v77, v77, v157
	v_mul_f32_e32 v78, v78, v157
	v_mul_f32_e32 v79, v79, v157
	v_lshlrev_b32_e32 v196, 16, v234
	v_and_b32_e32 v197, 0xffff0000, v234
	v_lshlrev_b32_e32 v198, 16, v235
	v_and_b32_e32 v199, 0xffff0000, v235
	v_mul_f32_e32 v76, v76, v196
	v_mul_f32_e32 v77, v77, v197
	v_mul_f32_e32 v78, v78, v198
	v_mul_f32_e32 v79, v79, v199
	v_cvt_pk_bf16_f32 v76, v76, v77
	v_cvt_pk_bf16_f32 v77, v78, v79
	global_store_dwordx2 v168, v[76:77], s[56:57] offset:48
	s_waitcnt vmcnt(15)
	v_mul_f32_e32 v80, v80, v157
	v_mul_f32_e32 v81, v81, v157
	v_mul_f32_e32 v82, v82, v157
	v_mul_f32_e32 v83, v83, v157
	v_lshlrev_b32_e32 v196, 16, v236
	v_and_b32_e32 v197, 0xffff0000, v236
	v_lshlrev_b32_e32 v198, 16, v237
	v_and_b32_e32 v199, 0xffff0000, v237
	v_mul_f32_e32 v80, v80, v196
	v_mul_f32_e32 v81, v81, v197
	v_mul_f32_e32 v82, v82, v198
	v_mul_f32_e32 v83, v83, v199
	v_cvt_pk_bf16_f32 v80, v80, v81
	v_cvt_pk_bf16_f32 v81, v82, v83
	global_store_dwordx2 v168, v[80:81], s[56:57] offset:64
	s_waitcnt vmcnt(15)
	v_mul_f32_e32 v84, v84, v157
	v_mul_f32_e32 v85, v85, v157
	v_mul_f32_e32 v86, v86, v157
	v_mul_f32_e32 v87, v87, v157
	v_lshlrev_b32_e32 v196, 16, v238
	v_and_b32_e32 v197, 0xffff0000, v238
	v_lshlrev_b32_e32 v198, 16, v239
	v_and_b32_e32 v199, 0xffff0000, v239
	v_mul_f32_e32 v84, v84, v196
	v_mul_f32_e32 v85, v85, v197
	v_mul_f32_e32 v86, v86, v198
	v_mul_f32_e32 v87, v87, v199
	v_cvt_pk_bf16_f32 v84, v84, v85
	v_cvt_pk_bf16_f32 v85, v86, v87
	global_store_dwordx2 v168, v[84:85], s[56:57] offset:80
	s_waitcnt vmcnt(15)
	v_mul_f32_e32 v88, v88, v157
	v_mul_f32_e32 v89, v89, v157
	v_mul_f32_e32 v90, v90, v157
	v_mul_f32_e32 v91, v91, v157
	v_lshlrev_b32_e32 v196, 16, v240
	v_and_b32_e32 v197, 0xffff0000, v240
	v_lshlrev_b32_e32 v198, 16, v241
	v_and_b32_e32 v199, 0xffff0000, v241
	v_mul_f32_e32 v88, v88, v196
	v_mul_f32_e32 v89, v89, v197
	v_mul_f32_e32 v90, v90, v198
	v_mul_f32_e32 v91, v91, v199
	v_cvt_pk_bf16_f32 v88, v88, v89
	v_cvt_pk_bf16_f32 v89, v90, v91
	global_store_dwordx2 v168, v[88:89], s[56:57] offset:96
	s_waitcnt vmcnt(15)
	v_mul_f32_e32 v92, v92, v157
	v_mul_f32_e32 v93, v93, v157
	v_mul_f32_e32 v94, v94, v157
	v_mul_f32_e32 v95, v95, v157
	v_lshlrev_b32_e32 v196, 16, v242
	v_and_b32_e32 v197, 0xffff0000, v242
	v_lshlrev_b32_e32 v198, 16, v243
	v_and_b32_e32 v199, 0xffff0000, v243
	v_mul_f32_e32 v92, v92, v196
	v_mul_f32_e32 v93, v93, v197
	v_mul_f32_e32 v94, v94, v198
	v_mul_f32_e32 v95, v95, v199
	v_cvt_pk_bf16_f32 v92, v92, v93
	v_cvt_pk_bf16_f32 v93, v94, v95
	global_store_dwordx2 v168, v[92:93], s[56:57] offset:112
	s_branch .Lat_ret_band
